# per-XCD start jitter (0..3 us) in front of the DeltaNet part-1 and elem phases, on top of stag2
# speedup vs baseline: 1.0052x; 1.0037x over previous
.LBB0_272:
	s_or_b64 exec, exec, s[0:1]
	v_mov_b32_e32 v0, v154
	s_waitcnt lgkmcnt(0)
	s_barrier
	v_readlane_b32 s8, v253, 0
	s_and_b32 s8, s8, 7
	s_cmp_eq_u32 s8, 0
	s_cbranch_scc1 .Ljit_skip_p6
.Ljit_loop_p6:
	s_sleep 16
	s_sub_u32 s8, s8, 1
	s_cmp_lg_u32 s8, 0
	s_cbranch_scc1 .Ljit_loop_p6
.Ljit_skip_p6:
	v_readlane_b32 s0, v253, 0
	v_lshrrev_b32_e32 v0, 8, v0
	v_mul_u32_u24_e32 v122, 0x12000, v0
	v_mov_b32_e32 v0, v154
	s_lshl_b32 s4, s0, 1
	v_readfirstlane_b32 s1, v0
	s_ashr_i32 s1, s1, 8
	s_add_i32 s26, s1, s4
	s_cmpk_gt_i32 s26, 0x7ff
	s_cbranch_scc1 .LBB0_362
	v_readlane_b32 s4, v254, 57
	s_lshl_b32 s5, s4, 6
	v_writelane_b32 v254, s5, 61
	s_lshl_b32 s4, s4, 3
	s_lshl_b32 s0, s0, 7
	s_lshl_b32 s1, s1, 6
	v_add_u32_e32 v123, 0x8800, v122
	v_add_u32_e32 v124, 0xcc00, v122
	v_add_u32_e32 v125, 0x11000, v122
	v_add_u32_e32 v126, 0x11100, v122
	v_add_u32_e32 v127, 0x11200, v122
	v_writelane_b32 v254, s4, 62
	v_add_u32_e32 v128, 0x110fc, v122
	s_add_i32 s23, s0, s1
	s_branch .LBB0_276

.Ljit_skip_el:
	v_readlane_b32 s0, v253, 0
	v_and_b32_e32 v4, 0xff, v0
	v_mov_b32_e32 v0, v154
	s_lshl_b32 s0, s0, 1
	v_readfirstlane_b32 s1, v0
	s_ashr_i32 s1, s1, 8
	s_add_i32 s0, s1, s0
	s_ashr_i32 s1, s0, 31
	s_lshl_b64 s[4:5], s[0:1], 8
	v_mov_b64_e32 v[0:1], 0x7ffff
	v_cmp_gt_u64_e32 vcc, s[4:5], v[0:1]
	s_cbranch_vccnz .LBB0_505
	s_lshl_b64 s[0:1], s[0:1], 11
	v_readlane_b32 s6, v254, 7
	v_readlane_b32 s8, v254, 9
	v_readlane_b32 s10, v254, 38
	v_readlane_b32 s12, v254, 40
	v_readlane_b32 s26, v254, 53
	v_mov_b32_e32 v1, s5
	v_or_b32_e32 v0, s4, v4
	v_lshl_or_b32 v2, v4, 3, s0
	v_mov_b32_e32 v3, s1
	s_mov_b64 s[0:1], 0
	v_readlane_b32 s7, v254, 8
	v_readlane_b32 s9, v254, 10
	v_readlane_b32 s11, v254, 39
	v_readlane_b32 s13, v254, 41
	s_movk_i32 s14, 0x600
	v_readlane_b32 s27, v254, 54
